# static priority raise for waves 4-7 over the whole P2 phase (RG-LRU pass + attention)
# baseline (speedup 1.0000x reference)
; #define LAS __attribute__((address_space(3)))
; __device__ __forceinline__ KP kargs() { KP q = (KP)__builtin_amdgcn_kernarg_segment_ptr(); asm volatile("" : "+s"(q)); return q; }
; #define LRU_LOADX(it_) do { const int hd_ = (it_) & 15, bc_ = (it_) >> 4, c_ = bc_ % NCH, b_ = bc_ / NCH; _Pragma("unroll") for (int k = 0; k < 5; ++k) { const int pos = c_ * 64 + 2 * rg - 3 + k; \
;             xw[k] = (u32x4){0u, 0u, 0u, 0u}; if (pos >= 0) xw[k] = *(const u32x4*)(XRb + ((size_t)(b_ * TPAD + pos)) * 2048 + hd_ * 128 + chg * 8); } } while (0)
; __global__ void __launch_bounds__(512, 2) fwd_mega(Params P_by_kernarg) {
;     ...
;     if (IN(2)) {
;         const KP KA = kargs(); unsigned char* const ws = KA->ws;
;         LAS bf16_t* XB = (LAS bf16_t*)lds;
;         LAS float* A_s = (LAS float*)((LAS unsigned char*)lds + 17408); LAS float* B_s = A_s + 64 * 129;
;         LAS float* PAR = (LAS float*)((LAS unsigned char*)lds + 83456); LAS float* SEG = PAR + 1024;
;     ...
;         {
;         const int chg = tid & 15, rg = tid >> 4, tt = wave & 1, jt = wave >> 1, l31 = lane & 31, hi = lane >> 5;
;         int loaded_hd = -1; bf16x8 wrf[8], wif[8]; u32x4 xw[5];
;     ...
;         for (int rep_ = 0; rep_ < (PROBE_SUB == 1 ? 2 : 1); ++rep_) {
;         if (vcu < 2 * NCH * 16) LRU_LOADX(vcu);
.LBB0_320:
	s_cmp_lt_i32 s33, 3
	s_cselect_b64 s[4:5], -1, 0
	s_and_b64 s[8:9], s[4:5], s[2:3]
	s_andn2_b64 vcc, exec, s[8:9]
	s_cbranch_vccnz .LBB0_543
	s_cmp_ge_u32 s66, 4
	s_cbranch_scc0 .Lattn_prio_done
	s_setprio 1
.Lattn_prio_done:
	s_waitcnt lgkmcnt(0)
	s_mov_b64 s[10:11], s[0:1]
	s_load_dwordx2 s[34:35], s[10:11], 0xc0
	s_cmpk_lt_i32 s67, 0x820
	v_and_b32_e32 v26, 15, v1
	v_lshrrev_b32_e32 v197, 4, v1
	s_cselect_b64 s[4:5], -1, 0
	s_waitcnt lgkmcnt(0)
	s_add_u32 s2, s34, 0x23500000
	s_addc_u32 s3, s35, 0
	v_lshlrev_b32_e32 v164, 1, v197
	v_lshlrev_b32_e32 v2, 3, v26
	s_cmpk_gt_i32 s67, 0x81f
	v_add_u32_e32 v150, -3, v164
	v_mov_b32_e32 v35, 0
	v_lshlrev_b32_e32 v34, 1, v2
	s_cbranch_scc1 .LBB0_333
	s_ashr_i32 s6, s67, 4
	s_mul_hi_i32 s7, s6, 0x7e07e07f
	s_lshr_b32 s12, s7, 31
	s_ashr_i32 s7, s7, 5
	s_add_i32 s12, s7, s12
	s_mul_i32 s7, s12, 0x41
	s_sub_i32 s6, s6, s7
	s_lshl_b32 s13, s6, 6
	s_lshl_b32 s6, s67, 8
	s_and_b32 s6, s6, 0xf00
	s_add_u32 s6, s2, s6
	v_add_u32_e32 v23, s13, v150
	s_addc_u32 s7, s3, 0
	s_mulk_i32 s12, 0x1080
	v_lshl_add_u64 v[24:25], s[6:7], 0, v[34:35]
	v_cmp_lt_i32_e32 vcc, -1, v23
	v_mov_b32_e32 v6, v35
	v_mov_b32_e32 v7, v35
	v_mov_b32_e32 v8, v35
	v_mov_b32_e32 v9, v35
	s_and_saveexec_b64 s[6:7], vcc
	s_cbranch_execz .LBB0_324
	v_add_u32_e32 v2, s12, v23
	v_ashrrev_i32_e32 v3, 31, v2
	v_lshlrev_b64 v[2:3], 12, v[2:3]
	v_lshl_add_u64 v[2:3], v[24:25], 0, v[2:3]
	global_load_dwordx4 v[6:9], v[2:3], off
